# NSA item prologue: second head's q-row loads issued together with the first head's (prologue de-serialisation)
# baseline (speedup 1.0000x reference)
.LBB0_786:
	s_lshl_b32 s0, s90, 3
	s_or_b32 s68, s0, s70
	s_mul_hi_u32 s0, s68, 0x55555556
	s_lshl_b32 s93, s2, 1
	s_mul_i32 s1, s0, 3
	s_add_i32 s93, s93, s53
	s_sub_i32 s1, s68, s1
	s_sub_i32 s92, 63, s93
	s_lshl_b32 s1, s1, 2
	s_or_b32 s33, s1, s72
	s_lshl_b32 s1, s92, 6
	s_or_b32 s91, s1, s73
	v_or_b32_e32 v210, s91, v172
	v_ashrrev_i32_e32 v211, 31, v210
	v_lshlrev_b64 v[0:1], 8, v[210:211]
	v_lshl_add_u64 v[48:49], v[192:193], 0, v[0:1]
	flat_load_dwordx4 v[24:27], v[190:191] offset:64
	flat_load_dwordx4 v[28:31], v[190:191] offset:80
	flat_load_dwordx4 v[8:11], v[190:191] offset:192
	flat_load_dwordx4 v[12:15], v[190:191] offset:208
	flat_load_dwordx4 v[4:7], v[48:49] offset:128
	flat_load_dwordx4 v[66:69], v[48:49] offset:144
	flat_load_dwordx4 v[0:3], v[48:49] offset:160
	flat_load_dwordx4 v[72:75], v[48:49] offset:176
	s_lshl_b32 s62, s0, 12
	v_lshl_add_u64 v[212:213], v[210:211], 0, s[62:63]
	v_mad_u64_u32 v[56:57], s[0:1], v212, s77, v[188:189]
	v_mad_i32_i24 v57, v213, s77, v57
	s_lshl_b32 s62, s33, 7
	v_lshl_add_u64 v[16:17], v[56:57], 0, s[62:63]
	v_lshl_add_u64 v[70:71], v[16:17], 0, v[168:169]
	global_load_dwordx4 v[76:79], v[70:71], off offset:32
	global_load_dwordx4 v[80:83], v[70:71], off offset:96
	global_load_dwordx4 v[84:87], v[70:71], off
	global_load_dwordx4 v[88:91], v[70:71], off offset:64
	global_load_dwordx4 v[152:155], v[70:71], off offset:128
	global_load_dwordx4 v[156:159], v[70:71], off offset:160
	global_load_dwordx4 v[160:163], v[70:71], off offset:192
	global_load_dwordx4 v[236:239], v[70:71], off offset:224
	flat_load_dwordx4 v[44:47], v[190:191]
	flat_load_dwordx4 v[40:43], v[190:191] offset:16
	flat_load_dwordx4 v[36:39], v[190:191] offset:128
	flat_load_dwordx4 v[32:35], v[190:191] offset:144
	flat_load_dwordx4 v[20:23], v[48:49]
	flat_load_dwordx4 v[52:55], v[48:49] offset:16
	flat_load_dwordx4 v[16:19], v[48:49] offset:32
	s_nop 0
	flat_load_dwordx4 v[48:51], v[48:49] offset:48
	s_mul_i32 s62, s33, 3
	s_mov_b32 s69, s63
	s_waitcnt vmcnt(0) lgkmcnt(0)
	v_mov_b32_e32 v60, v24
	v_mov_b32_e32 v64, v28
	v_mov_b32_e32 v58, v8
	v_mov_b32_e32 v59, v10
	v_mov_b32_e32 v10, v9
	v_mov_b32_e32 v8, v3
	v_mov_b32_e32 v9, v75
	v_mov_b32_e32 v3, v74
	v_lshlrev_b32_e32 v75, 16, v85
	v_lshlrev_b32_e32 v74, 16, v84
	v_and_b32_e32 v85, 0xffff0000, v85
	v_and_b32_e32 v84, 0xffff0000, v84
	v_pk_mul_f32 v[112:113], v[74:75], v[74:75]
	v_pk_mul_f32 v[114:115], v[84:85], v[84:85]
	v_lshlrev_b32_e32 v93, 16, v81
	v_and_b32_e32 v81, 0xffff0000, v81
	v_add_f32_e32 v112, v112, v114
	v_mov_b32_e32 v62, v12
	v_mov_b32_e32 v63, v14
	v_mov_b32_e32 v14, v13
	v_mov_b32_e32 v12, v5
	v_mov_b32_e32 v13, v67
	v_mov_b32_e32 v5, v66
	v_mov_b32_e32 v66, v81
	v_mov_b32_e32 v67, v93
	v_lshlrev_b32_e32 v121, 16, v87
	v_lshlrev_b32_e32 v120, 16, v86
	v_add_f32_e32 v112, v113, v112
	v_pk_mul_f32 v[108:109], v[66:67], v[66:67]
	v_mov_b32_e32 v66, v44
	v_mov_b32_e32 v67, v46
	v_mov_b32_e32 v46, v45
	v_and_b32_e32 v87, 0xffff0000, v87
	v_and_b32_e32 v86, 0xffff0000, v86
	v_pk_mul_f32 v[44:45], v[120:121], v[120:121]
	v_add_f32_e32 v112, v115, v112
	v_pk_mul_f32 v[124:125], v[86:87], v[86:87]
	v_add_f32_e32 v44, v44, v112
	v_add_f32_e32 v44, v124, v44
	v_mov_b32_e32 v65, v30
	v_mov_b32_e32 v30, v29
	v_mov_b32_e32 v28, v1
	v_mov_b32_e32 v29, v73
	v_mov_b32_e32 v1, v72
	v_lshlrev_b32_e32 v73, 16, v77
	v_lshlrev_b32_e32 v72, 16, v76
	v_add_f32_e32 v44, v45, v44
	v_mov_b32_e32 v61, v26
	v_mov_b32_e32 v26, v25
	v_mov_b32_e32 v24, v7
	v_mov_b32_e32 v25, v69
	v_mov_b32_e32 v7, v68
	v_and_b32_e32 v77, 0xffff0000, v77
	v_and_b32_e32 v76, 0xffff0000, v76
	v_pk_mul_f32 v[68:69], v[72:73], v[72:73]
	v_add_f32_e32 v44, v125, v44
	v_pk_mul_f32 v[98:99], v[76:77], v[76:77]
	v_add_f32_e32 v44, v68, v44
	v_add_f32_e32 v44, v98, v44
	v_lshlrev_b32_e32 v95, 16, v79
	v_lshlrev_b32_e32 v94, 16, v78
	v_add_f32_e32 v44, v69, v44
	v_and_b32_e32 v79, 0xffff0000, v79
	v_and_b32_e32 v78, 0xffff0000, v78
	v_pk_mul_f32 v[100:101], v[94:95], v[94:95]
	v_add_f32_e32 v44, v99, v44
	v_pk_mul_f32 v[102:103], v[78:79], v[78:79]
	v_add_f32_e32 v44, v100, v44
	v_add_f32_e32 v44, v102, v44
	v_lshlrev_b32_e32 v111, 16, v89
	v_lshlrev_b32_e32 v110, 16, v88
	v_add_f32_e32 v44, v101, v44
	v_and_b32_e32 v89, 0xffff0000, v89
	v_and_b32_e32 v88, 0xffff0000, v88
	v_pk_mul_f32 v[116:117], v[110:111], v[110:111]
	v_add_f32_e32 v44, v103, v44
	v_pk_mul_f32 v[118:119], v[88:89], v[88:89]
	v_add_f32_e32 v44, v116, v44
	v_add_f32_e32 v44, v118, v44
	v_lshlrev_b32_e32 v123, 16, v91
	v_lshlrev_b32_e32 v122, 16, v90
	v_add_f32_e32 v44, v117, v44
	v_and_b32_e32 v91, 0xffff0000, v91
	v_and_b32_e32 v90, 0xffff0000, v90
	v_pk_mul_f32 v[126:127], v[122:123], v[122:123]
	v_add_f32_e32 v44, v119, v44
	v_pk_mul_f32 v[128:129], v[90:91], v[90:91]
	v_add_f32_e32 v44, v126, v44
	v_add_f32_e32 v44, v128, v44
	v_add_f32_e32 v44, v127, v44
	v_lshlrev_b32_e32 v92, 16, v80
	v_add_f32_e32 v44, v129, v44
	v_and_b32_e32 v80, 0xffff0000, v80
	v_fmac_f32_e32 v44, v92, v92
	v_lshlrev_b32_e32 v96, 16, v82
	v_and_b32_e32 v82, 0xffff0000, v82
	v_fmac_f32_e32 v44, v80, v80
	v_mov_b32_e32 v104, v82
	v_mov_b32_e32 v105, v96
	v_add_f32_e32 v44, v109, v44
	v_lshlrev_b32_e32 v97, 16, v83
	v_and_b32_e32 v83, 0xffff0000, v83
	v_pk_mul_f32 v[104:105], v[104:105], v[104:105]
	v_add_f32_e32 v44, v108, v44
	v_mov_b32_e32 v106, v83
	v_mov_b32_e32 v107, v97
	v_add_f32_e32 v44, v105, v44
	v_pk_mul_f32 v[106:107], v[106:107], v[106:107]
	v_add_f32_e32 v44, v104, v44
	v_add_f32_e32 v44, v107, v44
	v_add_f32_e32 v45, v106, v44
	ds_bpermute_b32 v98, v177, v45
	v_mov_b32_e32 v44, v21
	v_mov_b32_e32 v68, v36
	v_mov_b32_e32 v69, v38
	v_mov_b32_e32 v38, v37
	s_waitcnt lgkmcnt(0)
	v_add_f32_e32 v21, v45, v98
	v_fmamk_f32 v21, v21, 0x3c800000, v226
	v_mul_f32_e32 v36, 0x4f800000, v21
	v_cmp_gt_f32_e32 vcc, s79, v21
	v_mov_b32_e32 v45, v53
	s_nop 0
	v_cndmask_b32_e32 v36, v21, v36, vcc
	v_sqrt_f32_e32 v37, v36
	v_mov_b32_e32 v21, v52
	v_mov_b32_e32 v52, v23
	v_add_u32_e32 v23, -1, v37
	v_fma_f32 v53, -v23, v37, v36
	v_cmp_ge_f32_e64 s[0:1], 0, v53
	v_add_u32_e32 v53, 1, v37
	s_nop 0
	v_cndmask_b32_e64 v23, v37, v23, s[0:1]
	v_fma_f32 v37, -v53, v37, v36
	v_cmp_lt_f32_e64 s[0:1], 0, v37
	s_nop 1
	v_cndmask_b32_e64 v23, v23, v53, s[0:1]
	v_mul_f32_e32 v37, 0x37800000, v23
	v_cndmask_b32_e32 v23, v23, v37, vcc
	v_cmp_class_f32_e32 vcc, v36, v227
	v_mov_b32_e32 v53, v55
	v_mov_b32_e32 v37, 0
	v_cndmask_b32_e32 v36, v23, v36, vcc
	v_div_scale_f32 v98, s[0:1], v36, v36, s80
	v_rcp_f32_e32 v99, v98
	v_mov_b32_e32 v23, v54
	v_fma_f32 v54, -v98, v99, 1.0
	v_fmac_f32_e32 v99, v54, v99
	v_div_scale_f32 v54, vcc, s80, v36, s80
	v_mul_f32_e32 v55, v54, v99
	v_fma_f32 v100, -v98, v55, v54
	v_fmac_f32_e32 v55, v100, v99
	v_fma_f32 v54, -v98, v55, v54
	v_div_fmas_f32 v54, v54, v99, v55
	v_div_fixup_f32 v36, v54, v36, s80
	v_pk_mul_f32 v[54:55], v[66:67], v[36:37] op_sel_hi:[1,0]
	v_pk_mul_f32 v[100:101], v[46:47], v[36:37] op_sel_hi:[1,0]
	v_pk_mul_f32 v[74:75], v[54:55], v[74:75]
	v_mov_b32_e32 v55, v42
	v_mov_b32_e32 v42, v41
	v_mov_b32_e32 v54, v40
	v_pk_mul_f32 v[40:41], v[42:43], v[36:37] op_sel_hi:[1,0]
	v_pk_mul_f32 v[84:85], v[100:101], v[84:85]
	v_pk_mul_f32 v[86:87], v[40:41], v[86:87]
	v_pk_mul_f32 v[40:41], v[60:61], v[36:37] op_sel_hi:[1,0]
	v_pk_mul_f32 v[98:99], v[54:55], v[36:37] op_sel_hi:[1,0]
	v_pk_mul_f32 v[100:101], v[40:41], v[72:73]
	v_pk_mul_f32 v[40:41], v[64:65], v[36:37] op_sel_hi:[1,0]
	v_mov_b32_e32 v73, v34
	v_mov_b32_e32 v34, v33
	v_pk_mul_f32 v[94:95], v[40:41], v[94:95]
	v_pk_mul_f32 v[40:41], v[26:27], v[36:37] op_sel_hi:[1,0]
	v_mov_b32_e32 v72, v32
	v_pk_mul_f32 v[32:33], v[34:35], v[36:37] op_sel_hi:[1,0]
	v_pk_mul_f32 v[102:103], v[40:41], v[76:77]
	v_pk_mul_f32 v[40:41], v[30:31], v[36:37] op_sel_hi:[1,0]
	v_pk_mul_f32 v[90:91], v[32:33], v[90:91]
	v_pk_mul_f32 v[32:33], v[58:59], v[36:37] op_sel_hi:[1,0]
	v_pk_mul_f32 v[104:105], v[40:41], v[78:79]
	v_pk_mul_f32 v[40:41], v[68:69], v[36:37] op_sel_hi:[1,0]
	v_pk_mul_f32 v[92:93], v[32:33], v[92:93]
	v_pk_mul_f32 v[32:33], v[62:63], v[36:37] op_sel_hi:[1,0]
	v_pk_mul_f32 v[76:77], v[40:41], v[110:111]
	v_pk_mul_f32 v[40:41], v[72:73], v[36:37] op_sel_hi:[1,0]
	v_pk_mul_f32 v[106:107], v[32:33], v[96:97]
	v_pk_mul_f32 v[32:33], v[10:11], v[36:37] op_sel_hi:[1,0]
	v_pk_mul_f32 v[78:79], v[40:41], v[122:123]
	v_pk_mul_f32 v[40:41], v[38:39], v[36:37] op_sel_hi:[1,0]
	v_pk_mul_f32 v[108:109], v[32:33], v[80:81]
	v_pk_mul_f32 v[32:33], v[14:15], v[36:37] op_sel_hi:[1,0]
	v_pk_mul_f32 v[88:89], v[40:41], v[88:89]
	v_pk_mul_f32 v[110:111], v[32:33], v[82:83]
	v_pk_mul_f32 v[32:33], v[20:21], v[76:77]
	v_pk_mul_f32 v[80:81], v[6:7], v[108:109]
	v_pk_fma_f32 v[112:113], v[44:45], v[74:75], v[32:33]
	v_pk_mul_f32 v[32:33], v[22:23], v[88:89]
	v_pk_mul_f32 v[98:99], v[98:99], v[120:121]
	v_pk_fma_f32 v[114:115], v[52:53], v[84:85], v[32:33]
	v_mov_b32_e32 v32, v17
	v_mov_b32_e32 v17, v48
	v_mov_b32_e32 v33, v49
	v_pk_mul_f32 v[40:41], v[16:17], v[78:79]
	v_pk_fma_f32 v[118:119], v[24:25], v[102:103], v[80:81]
	v_pk_mul_f32 v[80:81], v[0:1], v[106:107]
	v_pk_mul_f32 v[76:77], v[44:45], v[76:77]
	v_pk_fma_f32 v[116:117], v[32:33], v[98:99], v[40:41]
	v_mov_b32_e32 v40, v19
	v_mov_b32_e32 v41, v51
	v_pk_fma_f32 v[120:121], v[28:29], v[94:95], v[80:81]
	v_pk_mul_f32 v[80:81], v[2:3], v[110:111]
	v_pk_fma_f32 v[74:75], v[20:21], v[74:75], v[76:77] neg_lo:[0,0,1] neg_hi:[0,0,1]
	v_pk_mul_f32 v[76:77], v[52:53], v[88:89]
	v_mov_b32_e32 v19, v50
	v_pk_fma_f32 v[122:123], v[8:9], v[104:105], v[80:81]
	v_pk_fma_f32 v[76:77], v[22:23], v[84:85], v[76:77] neg_lo:[0,0,1] neg_hi:[0,0,1]
	v_pk_mul_f32 v[80:81], v[40:41], v[90:91]
	v_pk_mul_f32 v[78:79], v[32:33], v[78:79]
	v_pk_fma_f32 v[80:81], v[18:19], v[86:87], v[80:81] neg_lo:[0,0,1] neg_hi:[0,0,1]
	v_bfe_u32 v84, v76, 16, 1
	v_pk_mul_f32 v[48:49], v[18:19], v[90:91]
	v_pk_fma_f32 v[78:79], v[16:17], v[98:99], v[78:79] neg_lo:[0,0,1] neg_hi:[0,0,1]
	v_bfe_u32 v36, v81, 16, 1
	v_bfe_u32 v82, v80, 16, 1
	v_bfe_u32 v83, v77, 16, 1
	v_add3_u32 v90, v76, v84, s81
	v_bfe_u32 v76, v74, 16, 1
	v_add3_u32 v91, v77, v83, s81
	v_add3_u32 v96, v80, v82, s81
	v_add3_u32 v36, v81, v36, s81
	v_bfe_u32 v77, v75, 16, 1
	v_bfe_u32 v80, v78, 16, 1
	v_bfe_u32 v81, v79, 16, 1
	v_add3_u32 v74, v74, v76, s81
	v_add3_u32 v97, v79, v81, s81
	v_add3_u32 v82, v78, v80, s81
	v_add3_u32 v83, v75, v77, s81
	v_lshrrev_b32_e32 v124, 16, v74
	v_mov_b32_e32 v74, v152
	v_mov_b32_e32 v75, v153
	v_mov_b32_e32 v76, v154
	v_mov_b32_e32 v77, v155
	v_mov_b32_e32 v78, v156
	v_mov_b32_e32 v79, v157
	v_mov_b32_e32 v80, v158
	v_mov_b32_e32 v81, v159
	v_pk_fma_f32 v[50:51], v[40:41], v[86:87], v[48:49]
	v_lshrrev_b32_e32 v125, 16, v83
	v_lshrrev_b32_e32 v98, 16, v82
	v_mov_b32_e32 v82, v160
	v_mov_b32_e32 v83, v161
	v_mov_b32_e32 v84, v162
	v_mov_b32_e32 v85, v163
	v_mov_b32_e32 v86, v236
	v_mov_b32_e32 v87, v237
	v_mov_b32_e32 v88, v238
	v_mov_b32_e32 v89, v239
	v_lshrrev_b32_e32 v70, 16, v97
	v_pk_mul_f32 v[48:49], v[4:5], v[92:93]
	v_and_or_b32 v99, v36, s78, v70
	v_and_or_b32 v98, v96, s78, v98
	v_and_or_b32 v97, v91, s78, v125
	v_and_or_b32 v96, v90, s78, v124
	v_pk_mul_f32 v[70:71], v[12:13], v[92:93]
	v_pk_mul_f32 v[90:91], v[24:25], v[108:109]
	v_pk_mul_f32 v[92:93], v[28:29], v[106:107]
	v_pk_fma_f32 v[90:91], v[6:7], v[102:103], v[90:91] neg_lo:[0,0,1] neg_hi:[0,0,1]
	v_pk_fma_f32 v[92:93], v[0:1], v[94:95], v[92:93] neg_lo:[0,0,1] neg_hi:[0,0,1]
	v_pk_mul_f32 v[94:95], v[8:9], v[110:111]
	v_bfe_u32 v102, v90, 16, 1
	v_pk_fma_f32 v[94:95], v[2:3], v[104:105], v[94:95] neg_lo:[0,0,1] neg_hi:[0,0,1]
	v_pk_fma_f32 v[48:49], v[12:13], v[100:101], v[48:49]
	v_pk_fma_f32 v[70:71], v[4:5], v[100:101], v[70:71] neg_lo:[0,0,1] neg_hi:[0,0,1]
	v_bfe_u32 v100, v94, 16, 1
	v_add3_u32 v90, v90, v102, s81
	v_bfe_u32 v102, v93, 16, 1
	v_bfe_u32 v36, v95, 16, 1
	v_add3_u32 v94, v94, v100, s81
	v_bfe_u32 v100, v71, 16, 1
	v_add3_u32 v93, v93, v102, s81
	v_bfe_u32 v101, v91, 16, 1
	v_add3_u32 v36, v95, v36, s81
	v_bfe_u32 v95, v70, 16, 1
	v_add3_u32 v71, v71, v100, s81
	v_lshrrev_b32_e32 v93, 16, v93
	v_add3_u32 v91, v91, v101, s81
	v_bfe_u32 v101, v92, 16, 1
	v_add3_u32 v70, v70, v95, s81
	v_lshrrev_b32_e32 v71, 16, v71
	v_and_or_b32 v103, v36, s78, v93
	v_bfe_u32 v36, v51, 16, 1
	v_add3_u32 v92, v92, v101, s81
	v_lshrrev_b32_e32 v70, 16, v70
	v_and_or_b32 v101, v91, s78, v71
	v_add3_u32 v36, v51, v36, s81
	v_bfe_u32 v51, v112, 16, 1
	v_bfe_u32 v91, v116, 16, 1
	v_and_or_b32 v100, v90, s78, v70
	v_bfe_u32 v70, v50, 16, 1
	v_bfe_u32 v90, v114, 16, 1
	v_add3_u32 v91, v116, v91, s81
	v_add3_u32 v51, v112, v51, s81
	v_add3_u32 v90, v114, v90, s81
	v_add3_u32 v50, v50, v70, s81
	v_lshrrev_b32_e32 v51, 16, v51
	v_lshrrev_b32_e32 v91, 16, v91
	v_and_or_b32 v106, v50, s78, v91
	v_and_or_b32 v104, v90, s78, v51
	v_bfe_u32 v50, v122, 16, 1
	v_bfe_u32 v51, v119, 16, 1
	v_add3_u32 v145, v119, v51, s81
	v_add3_u32 v146, v122, v50, s81
	v_bfe_u32 v50, v120, 16, 1
	v_bfe_u32 v51, v121, 16, 1
	v_add3_u32 v149, v121, v51, s81
	v_add3_u32 v150, v120, v50, s81
	v_bfe_u32 v70, v113, 16, 1
	v_lshrrev_b32_e32 v92, 16, v92
	v_bfe_u32 v71, v115, 16, 1
	v_add3_u32 v70, v113, v70, s81
	v_and_or_b32 v102, v94, s78, v92
	v_add3_u32 v71, v115, v71, s81
	v_bfe_u32 v92, v117, 16, 1
	v_lshrrev_b32_e32 v70, 16, v70
	v_add3_u32 v92, v117, v92, s81
	v_and_or_b32 v105, v71, s78, v70
	v_bfe_u32 v70, v118, 16, 1
	v_lshrrev_b32_e32 v92, 16, v92
	v_add3_u32 v144, v118, v70, s81
	v_and_or_b32 v107, v36, s78, v92
	v_bfe_u32 v36, v123, 16, 1
	s_waitcnt vmcnt(3)
	v_lshlrev_b32_e32 v121, 16, v75
	v_lshlrev_b32_e32 v120, 16, v74
	v_and_b32_e32 v75, 0xffff0000, v75
	v_and_b32_e32 v74, 0xffff0000, v74
	v_pk_mul_f32 v[124:125], v[120:121], v[120:121]
	v_pk_mul_f32 v[126:127], v[74:75], v[74:75]
	v_lshlrev_b32_e32 v133, 16, v77
	v_add_f32_e32 v124, v124, v126
	v_lshlrev_b32_e32 v132, 16, v76
	v_add_f32_e32 v124, v125, v124
	v_and_b32_e32 v77, 0xffff0000, v77
	v_and_b32_e32 v76, 0xffff0000, v76
	v_pk_mul_f32 v[136:137], v[132:133], v[132:133]
	v_add_f32_e32 v124, v127, v124
	v_pk_mul_f32 v[138:139], v[76:77], v[76:77]
	v_add_f32_e32 v124, v136, v124
	v_add_f32_e32 v124, v138, v124
	s_waitcnt vmcnt(2)
	v_lshlrev_b32_e32 v51, 16, v79
	v_lshlrev_b32_e32 v50, 16, v78
	v_add_f32_e32 v124, v137, v124
	v_and_b32_e32 v71, 0xffff0000, v79
	v_and_b32_e32 v70, 0xffff0000, v78
	v_pk_mul_f32 v[90:91], v[50:51], v[50:51]
	v_add_f32_e32 v124, v139, v124
	v_pk_mul_f32 v[92:93], v[70:71], v[70:71]
	v_add_f32_e32 v90, v90, v124
	v_add_f32_e32 v90, v92, v90
	v_lshlrev_b32_e32 v113, 16, v81
	v_lshlrev_b32_e32 v112, 16, v80
	v_add_f32_e32 v90, v91, v90
	v_and_b32_e32 v81, 0xffff0000, v81
	v_and_b32_e32 v80, 0xffff0000, v80
	v_pk_mul_f32 v[108:109], v[112:113], v[112:113]
	v_add_f32_e32 v90, v93, v90
	v_pk_mul_f32 v[110:111], v[80:81], v[80:81]
	v_add_f32_e32 v90, v108, v90
	v_add_f32_e32 v90, v110, v90
	v_add3_u32 v36, v123, v36, s81
	s_waitcnt vmcnt(1)
	v_lshlrev_b32_e32 v123, 16, v83
	v_lshlrev_b32_e32 v122, 16, v82
	v_add_f32_e32 v90, v109, v90
	v_and_b32_e32 v83, 0xffff0000, v83
	v_and_b32_e32 v82, 0xffff0000, v82
	v_pk_mul_f32 v[128:129], v[122:123], v[122:123]
	v_add_f32_e32 v90, v111, v90
	v_pk_mul_f32 v[130:131], v[82:83], v[82:83]
	v_add_f32_e32 v90, v128, v90
	v_add_f32_e32 v90, v130, v90
	v_lshlrev_b32_e32 v135, 16, v85
	v_lshlrev_b32_e32 v134, 16, v84
	v_add_f32_e32 v90, v129, v90
	v_and_b32_e32 v85, 0xffff0000, v85
	v_and_b32_e32 v84, 0xffff0000, v84
	v_pk_mul_f32 v[140:141], v[134:135], v[134:135]
	v_add_f32_e32 v90, v131, v90
	v_pk_mul_f32 v[142:143], v[84:85], v[84:85]
	v_add_f32_e32 v90, v140, v90
	v_add_f32_e32 v90, v142, v90
	v_add_f32_e32 v90, v141, v90
	s_waitcnt vmcnt(0)
	v_lshlrev_b32_e32 v79, 16, v87
	v_lshlrev_b32_e32 v78, 16, v86
	v_and_b32_e32 v87, 0xffff0000, v87
	v_add_f32_e32 v90, v143, v90
	v_and_b32_e32 v86, 0xffff0000, v86
	v_mov_b32_e32 v94, v87
	v_mov_b32_e32 v95, v79
	v_fmac_f32_e32 v90, v78, v78
	v_pk_mul_f32 v[94:95], v[94:95], v[94:95]
	v_lshlrev_b32_e32 v114, 16, v88
	v_and_b32_e32 v88, 0xffff0000, v88
	v_fmac_f32_e32 v90, v86, v86
	v_mov_b32_e32 v116, v88
	v_mov_b32_e32 v117, v114
	v_add_f32_e32 v90, v95, v90
	v_lshlrev_b32_e32 v115, 16, v89
	v_and_b32_e32 v89, 0xffff0000, v89
	v_pk_mul_f32 v[116:117], v[116:117], v[116:117]
	v_add_f32_e32 v90, v94, v90
	v_mov_b32_e32 v118, v89
	v_mov_b32_e32 v119, v115
	v_add_f32_e32 v90, v117, v90
	v_pk_mul_f32 v[118:119], v[118:119], v[118:119]
	v_add_f32_e32 v90, v116, v90
	v_add_f32_e32 v90, v119, v90
	v_add_f32_e32 v90, v118, v90
	ds_bpermute_b32 v91, v177, v90
	v_lshrrev_b32_e32 v93, 16, v149
	v_and_or_b32 v111, v36, s78, v93
	v_bfe_u32 v147, v48, 16, 1
	v_add3_u32 v48, v48, v147, s81
	s_waitcnt lgkmcnt(0)
	v_add_f32_e32 v90, v90, v91
	v_fmamk_f32 v90, v90, 0x3c800000, v226
	v_mul_f32_e32 v91, 0x4f800000, v90
	v_cmp_gt_f32_e32 vcc, s79, v90
	v_bfe_u32 v148, v49, 16, 1
	v_lshrrev_b32_e32 v48, 16, v48
	v_cndmask_b32_e32 v90, v90, v91, vcc
	v_sqrt_f32_e32 v91, v90
	v_add3_u32 v49, v49, v148, s81
	v_and_or_b32 v108, v144, s78, v48
	v_lshrrev_b32_e32 v49, 16, v49
	v_add_u32_e32 v36, -1, v91
	v_fma_f32 v93, -v36, v91, v90
	v_cmp_ge_f32_e64 s[0:1], 0, v93
	v_add_u32_e32 v93, 1, v91
	v_lshrrev_b32_e32 v92, 16, v150
	v_cndmask_b32_e64 v36, v91, v36, s[0:1]
	v_fma_f32 v91, -v93, v91, v90
	v_cmp_lt_f32_e64 s[0:1], 0, v91
	v_and_or_b32 v109, v145, s78, v49
	v_and_or_b32 v110, v146, s78, v92
	v_cndmask_b32_e64 v36, v36, v93, s[0:1]
	v_mul_f32_e32 v91, 0x37800000, v36
	v_cndmask_b32_e32 v36, v36, v91, vcc
	v_cmp_class_f32_e32 vcc, v90, v227
	s_nop 1
	v_cndmask_b32_e32 v36, v36, v90, vcc
	v_div_scale_f32 v90, s[0:1], v36, v36, s80
	v_rcp_f32_e32 v91, v90
	s_lshl_b64 s[0:1], s[68:69], 15
	v_lshl_add_u64 v[214:215], v[196:197], 0, s[0:1]
	s_ashr_i32 s0, s91, 4
	v_fma_f32 v48, -v90, v91, 1.0
	v_fmac_f32_e32 v91, v48, v91
	v_div_scale_f32 v48, vcc, s80, v36, s80
	v_mul_f32_e32 v49, v48, v91
	v_fma_f32 v92, -v90, v49, v48
	v_fmac_f32_e32 v49, v92, v91
	v_fma_f32 v48, -v90, v49, v48
	v_div_fmas_f32 v48, v48, v91, v49
	v_div_fixup_f32 v36, v48, v36, s80
	v_pk_mul_f32 v[10:11], v[10:11], v[36:37] op_sel_hi:[1,0]
	v_pk_mul_f32 v[60:61], v[60:61], v[36:37] op_sel_hi:[1,0]
	v_pk_mul_f32 v[26:27], v[26:27], v[36:37] op_sel_hi:[1,0]
	v_pk_mul_f32 v[58:59], v[58:59], v[36:37] op_sel_hi:[1,0]
	v_pk_mul_f32 v[62:63], v[62:63], v[36:37] op_sel_hi:[1,0]
	v_pk_mul_f32 v[10:11], v[10:11], v[86:87]
	v_pk_mul_f32 v[50:51], v[60:61], v[50:51]
	v_pk_mul_f32 v[60:61], v[64:65], v[36:37] op_sel_hi:[1,0]
	v_pk_mul_f32 v[26:27], v[26:27], v[70:71]
	v_pk_mul_f32 v[58:59], v[58:59], v[78:79]
	v_pk_mul_f32 v[62:63], v[62:63], v[114:115]
	v_pk_mul_f32 v[78:79], v[6:7], v[10:11]
	v_pk_mul_f32 v[10:11], v[24:25], v[10:11]
	v_pk_mul_f32 v[60:61], v[60:61], v[112:113]
	v_pk_mul_f32 v[30:31], v[30:31], v[36:37] op_sel_hi:[1,0]
	v_pk_fma_f32 v[6:7], v[6:7], v[26:27], v[10:11] neg_lo:[0,0,1] neg_hi:[0,0,1]
	v_pk_mul_f32 v[10:11], v[28:29], v[62:63]
	v_pk_mul_f32 v[48:49], v[66:67], v[36:37] op_sel_hi:[1,0]
	v_pk_mul_f32 v[30:31], v[30:31], v[80:81]
	v_pk_mul_f32 v[64:65], v[68:69], v[36:37] op_sel_hi:[1,0]
	v_pk_mul_f32 v[66:67], v[72:73], v[36:37] op_sel_hi:[1,0]
	v_pk_mul_f32 v[80:81], v[0:1], v[62:63]
	v_pk_fma_f32 v[0:1], v[0:1], v[60:61], v[10:11] neg_lo:[0,0,1] neg_hi:[0,0,1]
	v_lshl_add_u64 v[10:11], s[62:63], 1, v[56:57]
	v_pk_mul_f32 v[54:55], v[54:55], v[36:37] op_sel_hi:[1,0]
	v_pk_mul_f32 v[64:65], v[64:65], v[122:123]
	v_pk_mul_f32 v[66:67], v[66:67], v[134:135]
	v_add_co_u32_e32 v10, vcc, s82, v10
	v_pk_mul_f32 v[48:49], v[48:49], v[120:121]
	v_pk_mul_f32 v[54:55], v[54:55], v[132:133]
	v_pk_mul_f32 v[68:69], v[20:21], v[64:65]
	v_pk_mul_f32 v[72:73], v[16:17], v[66:67]
	v_addc_co_u32_e32 v11, vcc, 0, v11, vcc
	v_pk_fma_f32 v[68:69], v[44:45], v[48:49], v[68:69]
	v_pk_fma_f32 v[72:73], v[32:33], v[54:55], v[72:73]
	v_pk_mul_f32 v[44:45], v[44:45], v[64:65]
	v_pk_mul_f32 v[32:33], v[32:33], v[66:67]
	flat_load_dwordx3 v[164:166], v[10:11] offset:256
	global_load_dwordx4 v[64:67], v[214:215], off
	global_load_dwordx4 v[136:139], v[214:215], off offset:1024
	global_load_dwordx4 v[132:135], v[214:215], off offset:2048
	global_load_dwordx4 v[128:131], v[214:215], off offset:3072
	v_pk_mul_f32 v[14:15], v[14:15], v[36:37] op_sel_hi:[1,0]
	v_pk_mul_f32 v[38:39], v[38:39], v[36:37] op_sel_hi:[1,0]
	v_pk_mul_f32 v[14:15], v[14:15], v[88:89]
	v_pk_mul_f32 v[42:43], v[42:43], v[36:37] op_sel_hi:[1,0]
	v_pk_mul_f32 v[38:39], v[38:39], v[82:83]
	v_pk_mul_f32 v[82:83], v[2:3], v[14:15]
	v_pk_mul_f32 v[42:43], v[42:43], v[76:77]
	v_pk_mul_f32 v[76:77], v[4:5], v[58:59]
	v_pk_fma_f32 v[82:83], v[8:9], v[30:31], v[82:83]
	v_pk_mul_f32 v[8:9], v[8:9], v[14:15]
	v_pk_fma_f32 v[76:77], v[12:13], v[50:51], v[76:77]
	v_pk_mul_f32 v[12:13], v[12:13], v[58:59]
	v_pk_fma_f32 v[2:3], v[2:3], v[30:31], v[8:9] neg_lo:[0,0,1] neg_hi:[0,0,1]
	v_pk_fma_f32 v[4:5], v[4:5], v[50:51], v[12:13] neg_lo:[0,0,1] neg_hi:[0,0,1]
	v_bfe_u32 v8, v3, 16, 1
	v_bfe_u32 v9, v2, 16, 1
	v_pk_mul_f32 v[34:35], v[34:35], v[36:37] op_sel_hi:[1,0]
	v_bfe_u32 v10, v7, 16, 1
	v_bfe_u32 v11, v6, 16, 1
	v_add3_u32 v2, v2, v9, s81
	v_add3_u32 v3, v3, v8, s81
	v_bfe_u32 v8, v4, 16, 1
	v_bfe_u32 v9, v5, 16, 1
	v_pk_mul_f32 v[46:47], v[46:47], v[36:37] op_sel_hi:[1,0]
	v_pk_mul_f32 v[34:35], v[34:35], v[84:85]
	v_add3_u32 v6, v6, v11, s81
	v_add3_u32 v7, v7, v10, s81
	v_bfe_u32 v10, v0, 16, 1
	v_bfe_u32 v11, v1, 16, 1
	v_add3_u32 v5, v5, v9, s81
	v_add3_u32 v4, v4, v8, s81
	v_pk_mul_f32 v[46:47], v[46:47], v[74:75]
	v_pk_mul_f32 v[70:71], v[22:23], v[38:39]
	v_pk_mul_f32 v[74:75], v[18:19], v[34:35]
	v_add3_u32 v1, v1, v11, s81
	v_add3_u32 v0, v0, v10, s81
	v_lshrrev_b32_e32 v4, 16, v4
	v_lshrrev_b32_e32 v5, 16, v5
	v_pk_fma_f32 v[70:71], v[52:53], v[46:47], v[70:71]
	v_pk_fma_f32 v[74:75], v[40:41], v[42:43], v[74:75]
	v_pk_mul_f32 v[38:39], v[52:53], v[38:39]
	v_pk_fma_f32 v[16:17], v[16:17], v[54:55], v[32:33] neg_lo:[0,0,1] neg_hi:[0,0,1]
	v_pk_mul_f32 v[32:33], v[40:41], v[34:35]
	v_lshrrev_b32_e32 v0, 16, v0
	v_lshrrev_b32_e32 v1, 16, v1
	v_and_or_b32 v117, v7, s78, v5
	v_and_or_b32 v116, v6, s78, v4
	v_bfe_u32 v4, v68, 16, 1
	v_bfe_u32 v5, v69, 16, 1
	v_bfe_u32 v6, v72, 16, 1
	v_bfe_u32 v7, v73, 16, 1
	v_pk_fma_f32 v[22:23], v[22:23], v[46:47], v[38:39] neg_lo:[0,0,1] neg_hi:[0,0,1]
	v_pk_fma_f32 v[18:19], v[18:19], v[42:43], v[32:33] neg_lo:[0,0,1] neg_hi:[0,0,1]
	v_and_or_b32 v119, v3, s78, v1
	v_and_or_b32 v118, v2, s78, v0
	v_bfe_u32 v0, v75, 16, 1
	v_bfe_u32 v1, v74, 16, 1
	v_bfe_u32 v2, v71, 16, 1
	v_bfe_u32 v3, v70, 16, 1
	v_add3_u32 v7, v73, v7, s81
	v_add3_u32 v6, v72, v6, s81
	v_add3_u32 v5, v69, v5, s81
	v_add3_u32 v4, v68, v4, s81
	v_pk_fma_f32 v[80:81], v[28:29], v[60:61], v[80:81]
	v_pk_fma_f32 v[20:21], v[20:21], v[48:49], v[44:45] neg_lo:[0,0,1] neg_hi:[0,0,1]
	v_bfe_u32 v32, v19, 16, 1
	v_bfe_u32 v33, v18, 16, 1
	v_bfe_u32 v34, v23, 16, 1
	v_bfe_u32 v35, v22, 16, 1
	v_add3_u32 v3, v70, v3, s81
	v_add3_u32 v2, v71, v2, s81
	v_add3_u32 v1, v74, v1, s81
	v_add3_u32 v0, v75, v0, s81
	v_lshrrev_b32_e32 v4, 16, v4
	v_lshrrev_b32_e32 v5, 16, v5
	v_lshrrev_b32_e32 v6, 16, v6
	v_lshrrev_b32_e32 v7, 16, v7
	v_pk_fma_f32 v[78:79], v[24:25], v[26:27], v[78:79]
	v_add3_u32 v22, v22, v35, s81
	v_add3_u32 v23, v23, v34, s81
	v_add3_u32 v18, v18, v33, s81
	v_add3_u32 v19, v19, v32, s81
	v_bfe_u32 v32, v20, 16, 1
	v_bfe_u32 v33, v21, 16, 1
	v_bfe_u32 v34, v16, 16, 1
	v_bfe_u32 v35, v17, 16, 1
	v_and_or_b32 v123, v0, s78, v7
	v_and_or_b32 v122, v1, s78, v6
	v_and_or_b32 v121, v2, s78, v5
	v_and_or_b32 v120, v3, s78, v4
	v_bfe_u32 v4, v76, 16, 1
	v_bfe_u32 v5, v77, 16, 1
	v_bfe_u32 v6, v80, 16, 1
	v_bfe_u32 v7, v81, 16, 1
	s_min_i32 s0, s0, 0xfe
	v_add3_u32 v17, v17, v35, s81
	v_add3_u32 v16, v16, v34, s81
	v_add3_u32 v21, v21, v33, s81
	v_add3_u32 v20, v20, v32, s81
	v_bfe_u32 v0, v83, 16, 1
	v_bfe_u32 v1, v82, 16, 1
	v_bfe_u32 v2, v79, 16, 1
	v_bfe_u32 v3, v78, 16, 1
	v_add3_u32 v7, v81, v7, s81
	v_add3_u32 v6, v80, v6, s81
	v_add3_u32 v5, v77, v5, s81
	v_add3_u32 v4, v76, v4, s81
	s_add_i32 s0, s0, 32
	v_lshrrev_b32_e32 v20, 16, v20
	v_lshrrev_b32_e32 v21, 16, v21
	v_lshrrev_b32_e32 v16, 16, v16
	v_lshrrev_b32_e32 v17, 16, v17
	v_add3_u32 v3, v78, v3, s81
	v_add3_u32 v2, v79, v2, s81
	v_add3_u32 v1, v82, v1, s81
	v_add3_u32 v0, v83, v0, s81
	v_lshrrev_b32_e32 v4, 16, v4
	v_lshrrev_b32_e32 v5, 16, v5
	v_lshrrev_b32_e32 v6, 16, v6
	v_lshrrev_b32_e32 v7, 16, v7
	s_ashr_i32 s94, s0, 5
	v_and_or_b32 v115, v19, s78, v17
	v_and_or_b32 v114, v18, s78, v16
	v_and_or_b32 v113, v23, s78, v21
	v_and_or_b32 v112, v22, s78, v20
	v_and_or_b32 v127, v0, s78, v7
	v_and_or_b32 v126, v1, s78, v6
	v_and_or_b32 v125, v2, s78, v5
	s_cmp_lt_i32 s94, 1
	v_and_or_b32 v124, v3, s78, v4
	s_cbranch_scc1 .LBB0_789
	v_mov_b32_e32 v36, 0
	s_mov_b32 s2, 0
	v_mov_b32_e32 v209, 0xf149f2ca
	s_movk_i32 s3, 0x800
	v_mov_b32_e32 v32, v171
	v_mov_b32_e32 v211, 0xf149f2ca
	v_mov_b32_e32 v37, v36
